# GLA prep item prologue: the 12 q/k/low loads (were 8 serial round trips) issued together with the w2 loads
# speedup vs baseline: 1.0363x; 1.0148x over previous
.LBB0_225:
	s_ashr_i32 s0, s58, 3
	s_mul_hi_i32 s1, s0, 0x38e38e39
	s_lshr_b32 s4, s1, 31
	s_ashr_i32 s1, s1, 3
	s_add_i32 s1, s1, s4
	s_mul_i32 s4, s1, 36
	s_sub_i32 s21, s0, s4
	s_lshl_b32 s0, s21, 6
	s_mul_hi_i32 s4, s1, 0x900
	s_mulk_i32 s1, 0x900
	s_ashr_i32 s5, s0, 31
	s_add_u32 s0, s1, s0
	s_addc_u32 s1, s4, s5
	v_lshl_add_u64 v[10:11], s[0:1], 0, v[28:29]
	s_and_b32 s4, s44, 0x180
	v_lshlrev_b64 v[2:3], 11, v[10:11]
	v_lshl_add_u64 v[2:3], s[46:47], 0, v[2:3]
	s_lshl_b32 s92, s4, 1
	v_lshl_add_u64 v[2:3], v[2:3], 0, s[92:93]
	v_lshl_add_u64 v[6:7], v[2:3], 0, v[0:1]
	s_waitcnt lgkmcnt(0)
	s_barrier
	global_load_dwordx4 v[200:203], v[6:7], off
	s_nop 0
	global_load_dwordx4 v[204:207], v[6:7], off offset:1024
	v_lshl_add_u64 v[12:13], s[0:1], 0, v[30:31]
	v_lshl_add_u64 v[14:15], s[0:1], 0, v[32:33]
	v_lshl_add_u64 v[16:17], s[0:1], 0, v[34:35]
	v_lshlrev_b64 v[2:3], 11, v[12:13]
	v_lshl_add_u64 v[2:3], s[46:47], 0, v[2:3]
	v_lshl_add_u64 v[2:3], v[2:3], 0, s[92:93]
	v_lshl_add_u64 v[2:3], v[2:3], 0, v[0:1]
	global_load_dwordx4 v[208:211], v[2:3], off
	global_load_dwordx4 v[212:215], v[2:3], off offset:1024
	v_lshlrev_b64 v[2:3], 11, v[14:15]
	v_lshl_add_u64 v[2:3], s[46:47], 0, v[2:3]
	v_lshl_add_u64 v[2:3], v[2:3], 0, s[92:93]
	v_lshl_add_u64 v[2:3], v[2:3], 0, v[0:1]
	global_load_dwordx4 v[216:219], v[2:3], off
	global_load_dwordx4 v[220:223], v[2:3], off offset:1024
	v_lshlrev_b64 v[2:3], 11, v[16:17]
	v_lshl_add_u64 v[2:3], s[46:47], 0, v[2:3]
	v_lshl_add_u64 v[2:3], v[2:3], 0, s[92:93]
	v_lshl_add_u64 v[2:3], v[2:3], 0, v[0:1]
	global_load_dwordx4 v[224:227], v[2:3], off
	global_load_dwordx4 v[228:231], v[2:3], off offset:1024
	s_and_b32 s90, s58, 1
	s_or_b32 s88, s90, s2
	s_ashr_i32 s89, s88, 31
	v_readlane_b32 s60, v253, 20
	s_lshl_b64 s[0:1], s[88:89], 15
	v_readlane_b32 s66, v253, 26
	v_readlane_b32 s67, v253, 27
	v_readlane_b32 s68, v253, 28
	v_readlane_b32 s69, v253, 29
	v_readlane_b32 s61, v253, 21
	v_readlane_b32 s62, v253, 22
	v_readlane_b32 s63, v253, 23
	v_readlane_b32 s64, v253, 24
	v_readlane_b32 s65, v253, 25
	v_readlane_b32 s70, v253, 30
	v_readlane_b32 s71, v253, 31
	v_readlane_b32 s72, v253, 32
	v_readlane_b32 s73, v253, 33
	v_readlane_b32 s74, v253, 34
	v_readlane_b32 s75, v253, 35
	s_lshl_b32 s92, s90, 5
	s_add_u32 s0, s66, s0
	s_addc_u32 s1, s67, s1
	s_lshl_b32 s5, s4, 2
	s_add_u32 s0, s0, s5
	s_addc_u32 s1, s1, 0
	v_lshl_add_u64 v[2:3], v[24:25], 0, s[92:93]
	v_lshlrev_b64 v[4:5], 6, v[10:11]
	v_lshl_add_u64 v[4:5], v[2:3], 0, v[4:5]
	global_load_ushort v232, v[4:5], off
	v_lshlrev_b64 v[4:5], 6, v[12:13]
	v_lshl_add_u64 v[4:5], v[2:3], 0, v[4:5]
	global_load_ushort v233, v[4:5], off
	v_lshlrev_b64 v[4:5], 6, v[14:15]
	v_lshl_add_u64 v[4:5], v[2:3], 0, v[4:5]
	global_load_ushort v234, v[4:5], off
	v_lshlrev_b64 v[4:5], 6, v[16:17]
	v_lshl_add_u64 v[2:3], v[2:3], 0, v[4:5]
	global_load_ushort v235, v[2:3], off
	v_mov_b32_e32 v3, v1
	v_lshlrev_b32_e32 v2, 2, v20
	v_lshl_add_u64 v[4:5], s[0:1], 0, v[2:3]
	global_load_dword v60, v2, s[0:1]
	global_load_dword v61, v2, s[0:1] offset:256
	global_load_dword v62, v2, s[0:1] offset:2048
	global_load_dword v63, v2, s[0:1] offset:2304
	v_add_co_u32_e64 v2, s[0:1], s85, v4
	s_nop 1
	v_addc_co_u32_e64 v3, s[0:1], 0, v5, s[0:1]
	v_add_co_u32_e64 v6, s[0:1], s37, v4
	s_nop 1
	v_addc_co_u32_e64 v7, s[0:1], 0, v5, s[0:1]
	global_load_dword v64, v[6:7], off offset:-4096
	global_load_dword v65, v[2:3], off offset:256
	global_load_dword v66, v[2:3], off offset:2048
	global_load_dword v67, v[2:3], off offset:2304
	global_load_dword v47, v[6:7], off
	global_load_dword v46, v[6:7], off offset:256
	global_load_dword v17, v[6:7], off offset:2048
	global_load_dword v16, v[6:7], off offset:2304
	v_add_co_u32_e64 v2, s[0:1], s33, v4
	s_nop 1
	v_addc_co_u32_e64 v3, s[0:1], 0, v5, s[0:1]
	s_movk_i32 s0, 0x4000
	s_nop 0
	v_add_co_u32_e64 v6, s[0:1], s0, v4
	s_nop 1
	v_addc_co_u32_e64 v7, s[0:1], 0, v5, s[0:1]
	s_movk_i32 s0, 0x5000
	global_load_dword v52, v[6:7], off offset:-4096
	global_load_dword v53, v[2:3], off offset:256
	global_load_dword v54, v[2:3], off offset:2048
	global_load_dword v55, v[2:3], off offset:2304
	global_load_dword v48, v[6:7], off
	global_load_dword v49, v[6:7], off offset:256
	global_load_dword v50, v[6:7], off offset:2048
	global_load_dword v51, v[6:7], off offset:2304
	v_add_co_u32_e64 v2, s[0:1], s0, v4
	s_nop 1
	v_addc_co_u32_e64 v3, s[0:1], 0, v5, s[0:1]
	s_movk_i32 s0, 0x6000
	s_nop 0
	v_add_co_u32_e64 v8, s[0:1], s0, v4
	s_nop 1
	v_addc_co_u32_e64 v9, s[0:1], 0, v5, s[0:1]
	s_movk_i32 s0, 0x7000
	global_load_dword v56, v[8:9], off offset:-4096
	global_load_dword v57, v[2:3], off offset:256
	global_load_dword v58, v[2:3], off offset:2048
	global_load_dword v59, v[2:3], off offset:2304
	global_load_dword v12, v[8:9], off
	global_load_dword v13, v[8:9], off offset:256
	global_load_dword v6, v[8:9], off offset:2048
	global_load_dword v7, v[8:9], off offset:2304
	v_add_co_u32_e64 v2, s[0:1], s0, v4
	s_nop 1
	v_addc_co_u32_e64 v3, s[0:1], 0, v5, s[0:1]
	s_lshl_b32 s0, s88, 9
	s_or_b32 s0, s0, s4
	global_load_dword v14, v[2:3], off
	global_load_dword v15, v[2:3], off offset:256
	global_load_dword v9, v[2:3], off offset:2048
	global_load_dword v10, v[2:3], off offset:2304
	v_or_b32_e32 v2, s0, v20
	v_ashrrev_i32_e32 v3, 31, v2
	v_lshl_add_u64 v[2:3], v[2:3], 2, s[68:69]
	global_load_dword v69, v[2:3], off
	global_load_dword v68, v[2:3], off offset:256
	s_waitcnt vmcnt(34)
	ds_write_b128 v82, v[200:203]
	ds_write_b128 v82, v[204:207] offset:16384
	ds_write_b128 v85, v[208:211]
	ds_write_b128 v85, v[212:215] offset:16384
	ds_write_b128 v88, v[216:219]
	ds_write_b128 v88, v[220:223] offset:16384
	ds_write_b128 v91, v[224:227]
	ds_write_b128 v91, v[228:231] offset:16384
	v_lshlrev_b32_e32 v236, 16, v232
	v_lshlrev_b32_e32 v237, 16, v233
	ds_write2st64_b32 v18, v236, v237 offset0:128 offset1:132
	v_lshlrev_b32_e32 v238, 16, v234
	v_lshlrev_b32_e32 v239, 16, v235
	ds_write2st64_b32 v18, v238, v239 offset0:136 offset1:140
	s_waitcnt lgkmcnt(0)
	s_barrier
	ds_read_b128 v[2:5], v19 offset:32768
	ds_read_b128 v[156:159], v19 offset:32784
	ds_read_b128 v[160:163], v19 offset:32800
	ds_read_b128 v[164:167], v19 offset:32816
	s_waitcnt vmcnt(1) lgkmcnt(3)
	v_fma_f32 v8, v60, v2, v69
	v_fmac_f32_e32 v8, v62, v3
	v_fmac_f32_e32 v8, v64, v4
	v_fmac_f32_e32 v8, v66, v5
	s_waitcnt lgkmcnt(2)
	v_fmac_f32_e32 v8, v47, v156
	v_fmac_f32_e32 v8, v17, v157
	v_fmac_f32_e32 v8, v52, v158
	v_fmac_f32_e32 v8, v54, v159
	s_waitcnt lgkmcnt(1)
	v_fmac_f32_e32 v8, v48, v160
	v_fmac_f32_e32 v8, v50, v161
	v_fmac_f32_e32 v8, v56, v162
	v_fmac_f32_e32 v8, v58, v163
	s_waitcnt lgkmcnt(0)
	v_fmac_f32_e32 v8, v12, v164
	v_fmac_f32_e32 v8, v6, v165
	s_waitcnt vmcnt(0)
	v_fma_f32 v2, v61, v2, v68
	v_fmac_f32_e32 v8, v14, v166
	v_fmac_f32_e32 v2, v63, v3
	v_fmac_f32_e32 v8, v9, v167
	v_fmac_f32_e32 v2, v65, v4
	v_mul_f32_e64 v4, |v8|, s84
	v_exp_f32_e32 v4, v4
	v_fmac_f32_e32 v2, v67, v5
	v_fmac_f32_e32 v2, v46, v156
	v_fmac_f32_e32 v2, v16, v157
	v_add_f32_e32 v4, 1.0, v4
	v_cmp_gt_f32_e64 s[0:1], s31, v4
	v_fmac_f32_e32 v2, v53, v158
	v_fmac_f32_e32 v2, v55, v159
	v_cndmask_b32_e64 v5, 0, 32, s[0:1]
	v_ldexp_f32 v4, v4, v5
	v_log_f32_e32 v4, v4
	v_fmac_f32_e32 v2, v49, v160
	v_fmac_f32_e32 v2, v51, v161
	v_fmac_f32_e32 v2, v57, v162
	v_mul_f32_e32 v5, 0x3f317217, v4
	v_fmac_f32_e32 v2, v59, v163
	v_fma_f32 v5, v4, s78, -v5
	v_fmac_f32_e32 v2, v13, v164
	v_fmac_f32_e32 v5, 0x3377d1cf, v4
	v_fmac_f32_e32 v2, v7, v165
	v_fmac_f32_e32 v5, 0x3f317217, v4
	v_cmp_lt_f32_e64 s[88:89], |v4|, s79
	v_fmac_f32_e32 v2, v15, v166
	v_fmac_f32_e32 v2, v10, v167
	v_cndmask_b32_e64 v4, v4, v5, s[88:89]
	v_cndmask_b32_e64 v5, 0, v198, s[0:1]
	v_min_f32_e32 v3, 0, v8
	v_sub_f32_e32 v4, v4, v5
	v_sub_f32_e32 v70, v3, v4
	v_min_f32_e32 v3, 0, v2
	v_mul_f32_e64 v2, |v2|, s84
	v_exp_f32_e32 v2, v2
	v_fma_f32 v11, v70, s10, 0
	v_add_f32_e32 v2, 1.0, v2
	v_cmp_gt_f32_e64 s[0:1], s31, v2
	s_nop 1
	v_cndmask_b32_e64 v4, 0, 32, s[0:1]
	v_ldexp_f32 v2, v2, v4
	v_log_f32_e32 v2, v2
	s_nop 0
	v_mul_f32_e32 v4, 0x3f317217, v2
	v_fma_f32 v4, v2, s78, -v4
	v_fmac_f32_e32 v4, 0x3377d1cf, v2
	v_fmac_f32_e32 v4, 0x3f317217, v2
	v_cmp_lt_f32_e64 s[88:89], |v2|, s79
	s_nop 1
	v_cndmask_b32_e64 v2, v2, v4, s[88:89]
	v_cndmask_b32_e64 v4, 0, v198, s[0:1]
	v_sub_f32_e32 v2, v2, v4
	v_sub_f32_e32 v71, v3, v2
	ds_read_b128 v[2:5], v19 offset:32832
	v_fma_f32 v8, v71, s10, 0
	s_waitcnt lgkmcnt(0)
	v_fma_f32 v155, v60, v2, v69
	v_fma_f32 v156, v61, v2, v68
	v_fmac_f32_e32 v155, v62, v3
	v_fmac_f32_e32 v156, v63, v3
	v_fmac_f32_e32 v155, v64, v4
	v_fmac_f32_e32 v156, v65, v4
	v_fmac_f32_e32 v155, v66, v5
	v_fmac_f32_e32 v156, v67, v5
	ds_read_b128 v[2:5], v19 offset:32848
	s_waitcnt lgkmcnt(0)
	v_fmac_f32_e32 v155, v47, v2
	v_fmac_f32_e32 v156, v46, v2
	v_fmac_f32_e32 v155, v17, v3
	v_fmac_f32_e32 v156, v16, v3
	v_fmac_f32_e32 v155, v52, v4
	v_fmac_f32_e32 v156, v53, v4
	v_fmac_f32_e32 v155, v54, v5
	v_fmac_f32_e32 v156, v55, v5
	ds_read_b128 v[2:5], v19 offset:32864
	s_waitcnt lgkmcnt(0)
	v_fmac_f32_e32 v155, v48, v2
	v_fmac_f32_e32 v156, v49, v2
	v_fmac_f32_e32 v155, v50, v3
	v_fmac_f32_e32 v156, v51, v3
	v_fmac_f32_e32 v155, v56, v4
	v_fmac_f32_e32 v156, v57, v4
	v_fmac_f32_e32 v155, v58, v5
	v_fmac_f32_e32 v156, v59, v5
	ds_read_b128 v[2:5], v19 offset:32880
	s_waitcnt lgkmcnt(0)
	v_fmac_f32_e32 v155, v12, v2
	v_fmac_f32_e32 v155, v6, v3
	v_fmac_f32_e32 v155, v14, v4
	v_fmac_f32_e32 v156, v13, v2
	v_fmac_f32_e32 v155, v9, v5
	v_fmac_f32_e32 v156, v7, v3
	v_mul_f32_e64 v3, |v155|, s84
	v_exp_f32_e32 v3, v3
	v_fmac_f32_e32 v156, v15, v4
	v_fmac_f32_e32 v156, v10, v5
	v_min_f32_e32 v2, 0, v155
	v_add_f32_e32 v3, 1.0, v3
	v_cmp_gt_f32_e64 s[0:1], s31, v3
	s_nop 1
	v_cndmask_b32_e64 v4, 0, 32, s[0:1]
	v_ldexp_f32 v3, v3, v4
	v_log_f32_e32 v3, v3
	s_nop 0
	v_mul_f32_e32 v4, 0x3f317217, v3
	v_fma_f32 v4, v3, s78, -v4
	v_fmac_f32_e32 v4, 0x3377d1cf, v3
	v_fmac_f32_e32 v4, 0x3f317217, v3
	v_cmp_lt_f32_e64 s[88:89], |v3|, s79
	s_nop 1
	v_cndmask_b32_e64 v3, v3, v4, s[88:89]
	v_cndmask_b32_e64 v4, 0, v198, s[0:1]
	v_sub_f32_e32 v3, v3, v4
	v_sub_f32_e32 v159, v2, v3
	v_mul_f32_e64 v3, |v156|, s84
	v_exp_f32_e32 v3, v3
	v_min_f32_e32 v2, 0, v156
	v_fmamk_f32 v156, v159, 0x3d800000, v11
	v_add_f32_e32 v3, 1.0, v3
	v_cmp_gt_f32_e64 s[0:1], s31, v3
	s_nop 1
	v_cndmask_b32_e64 v4, 0, 32, s[0:1]
	v_ldexp_f32 v3, v3, v4
	v_log_f32_e32 v3, v3
	s_nop 0
	v_mul_f32_e32 v4, 0x3f317217, v3
	v_fma_f32 v4, v3, s78, -v4
	v_fmac_f32_e32 v4, 0x3377d1cf, v3
	v_fmac_f32_e32 v4, 0x3f317217, v3
	v_cmp_lt_f32_e64 s[88:89], |v3|, s79
	s_nop 1
	v_cndmask_b32_e64 v3, v3, v4, s[88:89]
	v_cndmask_b32_e64 v4, 0, v198, s[0:1]
	v_sub_f32_e32 v3, v3, v4
	v_sub_f32_e32 v160, v2, v3
	ds_read_b128 v[2:5], v19 offset:32896
	v_fmamk_f32 v155, v160, 0x3d800000, v8
	s_waitcnt lgkmcnt(0)
	v_fma_f32 v157, v60, v2, v69
	v_fma_f32 v158, v61, v2, v68
	v_fmac_f32_e32 v157, v62, v3
	v_fmac_f32_e32 v158, v63, v3
	v_fmac_f32_e32 v157, v64, v4
	v_fmac_f32_e32 v158, v65, v4
	v_fmac_f32_e32 v157, v66, v5
	v_fmac_f32_e32 v158, v67, v5
	ds_read_b128 v[2:5], v19 offset:32912
	s_waitcnt lgkmcnt(0)
	v_fmac_f32_e32 v157, v47, v2
	v_fmac_f32_e32 v158, v46, v2
	v_fmac_f32_e32 v157, v17, v3
	v_fmac_f32_e32 v158, v16, v3
	v_fmac_f32_e32 v157, v52, v4
	v_fmac_f32_e32 v158, v53, v4
	v_fmac_f32_e32 v157, v54, v5
	v_fmac_f32_e32 v158, v55, v5
	ds_read_b128 v[2:5], v19 offset:32928
	s_waitcnt lgkmcnt(0)
	v_fmac_f32_e32 v157, v48, v2
	v_fmac_f32_e32 v158, v49, v2
	v_fmac_f32_e32 v157, v50, v3
	v_fmac_f32_e32 v158, v51, v3
	v_fmac_f32_e32 v157, v56, v4
	v_fmac_f32_e32 v158, v57, v4
	v_fmac_f32_e32 v157, v58, v5
	v_fmac_f32_e32 v158, v59, v5
	ds_read_b128 v[2:5], v19 offset:32944
	s_waitcnt lgkmcnt(0)
	v_fmac_f32_e32 v157, v12, v2
	v_fmac_f32_e32 v157, v6, v3
	v_fmac_f32_e32 v157, v14, v4
	v_fmac_f32_e32 v158, v13, v2
	v_fmac_f32_e32 v157, v9, v5
	v_fmac_f32_e32 v158, v7, v3
	v_mul_f32_e64 v3, |v157|, s84
	v_exp_f32_e32 v3, v3
	v_fmac_f32_e32 v158, v15, v4
	v_fmac_f32_e32 v158, v10, v5
	v_min_f32_e32 v2, 0, v157
	v_add_f32_e32 v3, 1.0, v3
	v_cmp_gt_f32_e64 s[0:1], s31, v3
	s_nop 1
	v_cndmask_b32_e64 v4, 0, 32, s[0:1]
	v_ldexp_f32 v3, v3, v4
	v_log_f32_e32 v3, v3
	s_nop 0
	v_mul_f32_e32 v4, 0x3f317217, v3
	v_fma_f32 v4, v3, s78, -v4
	v_fmac_f32_e32 v4, 0x3377d1cf, v3
	v_fmac_f32_e32 v4, 0x3f317217, v3
	v_cmp_lt_f32_e64 s[88:89], |v3|, s79
	s_nop 1
	v_cndmask_b32_e64 v3, v3, v4, s[88:89]
	v_cndmask_b32_e64 v4, 0, v198, s[0:1]
	v_sub_f32_e32 v3, v3, v4
	v_sub_f32_e32 v163, v2, v3
	v_mul_f32_e64 v3, |v158|, s84
	v_exp_f32_e32 v3, v3
	v_min_f32_e32 v2, 0, v158
	v_fmamk_f32 v158, v163, 0x3d800000, v156
	v_add_f32_e32 v3, 1.0, v3
	v_cmp_gt_f32_e64 s[0:1], s31, v3
	s_nop 1
	v_cndmask_b32_e64 v4, 0, 32, s[0:1]
	v_ldexp_f32 v3, v3, v4
	v_log_f32_e32 v3, v3
	s_nop 0
	v_mul_f32_e32 v4, 0x3f317217, v3
	v_fma_f32 v4, v3, s78, -v4
	v_fmac_f32_e32 v4, 0x3377d1cf, v3
	v_fmac_f32_e32 v4, 0x3f317217, v3
	v_cmp_lt_f32_e64 s[88:89], |v3|, s79
	s_nop 1
	v_cndmask_b32_e64 v3, v3, v4, s[88:89]
	v_cndmask_b32_e64 v4, 0, v198, s[0:1]
	v_sub_f32_e32 v3, v3, v4
	v_sub_f32_e32 v164, v2, v3
	ds_read_b128 v[2:5], v19 offset:32960
	v_fmamk_f32 v157, v164, 0x3d800000, v155
	s_waitcnt lgkmcnt(0)
	v_fma_f32 v161, v60, v2, v69
	v_fma_f32 v162, v61, v2, v68
	v_fmac_f32_e32 v161, v62, v3
	v_fmac_f32_e32 v162, v63, v3
	v_fmac_f32_e32 v161, v64, v4
	v_fmac_f32_e32 v162, v65, v4
	v_fmac_f32_e32 v161, v66, v5
	v_fmac_f32_e32 v162, v67, v5
	ds_read_b128 v[2:5], v19 offset:32976
	s_waitcnt lgkmcnt(0)
	v_fmac_f32_e32 v161, v47, v2
	v_fmac_f32_e32 v162, v46, v2
	v_fmac_f32_e32 v161, v17, v3
	v_fmac_f32_e32 v162, v16, v3
	v_fmac_f32_e32 v161, v52, v4
	v_fmac_f32_e32 v162, v53, v4
	v_fmac_f32_e32 v161, v54, v5
	v_fmac_f32_e32 v162, v55, v5
	ds_read_b128 v[2:5], v19 offset:32992
	s_waitcnt lgkmcnt(0)
	v_fmac_f32_e32 v161, v48, v2
	v_fmac_f32_e32 v162, v49, v2
	v_fmac_f32_e32 v161, v50, v3
	v_fmac_f32_e32 v162, v51, v3
	v_fmac_f32_e32 v161, v56, v4
	v_fmac_f32_e32 v162, v57, v4
	v_fmac_f32_e32 v161, v58, v5
	v_fmac_f32_e32 v162, v59, v5
	ds_read_b128 v[2:5], v19 offset:33008
	s_waitcnt lgkmcnt(0)
	v_fmac_f32_e32 v161, v12, v2
	v_fmac_f32_e32 v161, v6, v3
	v_fmac_f32_e32 v161, v14, v4
	v_fmac_f32_e32 v162, v13, v2
	v_fmac_f32_e32 v161, v9, v5
	v_fmac_f32_e32 v162, v7, v3
	v_mul_f32_e64 v3, |v161|, s84
	v_exp_f32_e32 v3, v3
	v_fmac_f32_e32 v162, v15, v4
	v_fmac_f32_e32 v162, v10, v5
	v_min_f32_e32 v2, 0, v161
	v_add_f32_e32 v3, 1.0, v3
	v_cmp_gt_f32_e64 s[0:1], s31, v3
	s_nop 1
	v_cndmask_b32_e64 v4, 0, 32, s[0:1]
	v_ldexp_f32 v3, v3, v4
	v_log_f32_e32 v3, v3
	s_nop 0
	v_mul_f32_e32 v4, 0x3f317217, v3
	v_fma_f32 v4, v3, s78, -v4
	v_fmac_f32_e32 v4, 0x3377d1cf, v3
	v_fmac_f32_e32 v4, 0x3f317217, v3
	v_cmp_lt_f32_e64 s[88:89], |v3|, s79
	s_nop 1
	v_cndmask_b32_e64 v3, v3, v4, s[88:89]
	v_cndmask_b32_e64 v4, 0, v198, s[0:1]
	v_sub_f32_e32 v3, v3, v4
	v_sub_f32_e32 v165, v2, v3
	v_mul_f32_e64 v3, |v162|, s84
	v_exp_f32_e32 v3, v3
	v_min_f32_e32 v2, 0, v162
	v_fmamk_f32 v162, v165, 0x3d800000, v158
	v_add_f32_e32 v3, 1.0, v3
	v_cmp_gt_f32_e64 s[0:1], s31, v3
	s_nop 1
	v_cndmask_b32_e64 v4, 0, 32, s[0:1]
	v_ldexp_f32 v3, v3, v4
	v_log_f32_e32 v3, v3
	s_nop 0
	v_mul_f32_e32 v4, 0x3f317217, v3
	v_fma_f32 v4, v3, s78, -v4
	v_fmac_f32_e32 v4, 0x3377d1cf, v3
	v_fmac_f32_e32 v4, 0x3f317217, v3
	v_cmp_lt_f32_e64 s[88:89], |v3|, s79
	s_nop 1
	v_cndmask_b32_e64 v3, v3, v4, s[88:89]
	v_cndmask_b32_e64 v4, 0, v198, s[0:1]
	v_sub_f32_e32 v3, v3, v4
	v_sub_f32_e32 v166, v2, v3
	ds_read_b128 v[2:5], v19 offset:33024
	v_fmamk_f32 v161, v166, 0x3d800000, v157
	s_waitcnt lgkmcnt(0)
	v_fma_f32 v168, v60, v2, v69
	v_fma_f32 v167, v61, v2, v68
	v_fmac_f32_e32 v168, v62, v3
	v_fmac_f32_e32 v167, v63, v3
	v_fmac_f32_e32 v168, v64, v4
	v_fmac_f32_e32 v167, v65, v4
	v_fmac_f32_e32 v168, v66, v5
	v_fmac_f32_e32 v167, v67, v5
	ds_read_b128 v[2:5], v19 offset:33040
	s_waitcnt lgkmcnt(0)
	v_fmac_f32_e32 v168, v47, v2
	v_fmac_f32_e32 v167, v46, v2
	v_fmac_f32_e32 v168, v17, v3
	v_fmac_f32_e32 v167, v16, v3
	v_fmac_f32_e32 v168, v52, v4
	v_fmac_f32_e32 v167, v53, v4
	v_fmac_f32_e32 v168, v54, v5
	v_fmac_f32_e32 v167, v55, v5
	ds_read_b128 v[2:5], v19 offset:33056
	s_waitcnt lgkmcnt(0)
	v_fmac_f32_e32 v168, v48, v2
	v_fmac_f32_e32 v167, v49, v2
	v_fmac_f32_e32 v168, v50, v3
	v_fmac_f32_e32 v167, v51, v3
	v_fmac_f32_e32 v168, v56, v4
	v_fmac_f32_e32 v167, v57, v4
	v_fmac_f32_e32 v168, v58, v5
	v_fmac_f32_e32 v167, v59, v5
	ds_read_b128 v[2:5], v19 offset:33072
	s_waitcnt lgkmcnt(0)
	v_fmac_f32_e32 v168, v12, v2
	v_fmac_f32_e32 v168, v6, v3
	v_fmac_f32_e32 v168, v14, v4
	v_fmac_f32_e32 v167, v13, v2
	v_fmac_f32_e32 v168, v9, v5
	v_fmac_f32_e32 v167, v7, v3
	v_mul_f32_e64 v3, |v168|, s84
	v_exp_f32_e32 v3, v3
	v_fmac_f32_e32 v167, v15, v4
	v_fmac_f32_e32 v167, v10, v5
	v_min_f32_e32 v2, 0, v168
	v_add_f32_e32 v3, 1.0, v3
	v_cmp_gt_f32_e64 s[0:1], s31, v3
	s_nop 1
	v_cndmask_b32_e64 v4, 0, 32, s[0:1]
	v_ldexp_f32 v3, v3, v4
	v_log_f32_e32 v3, v3
	s_nop 0
	v_mul_f32_e32 v4, 0x3f317217, v3
	v_fma_f32 v4, v3, s78, -v4
	v_fmac_f32_e32 v4, 0x3377d1cf, v3
	v_fmac_f32_e32 v4, 0x3f317217, v3
	v_cmp_lt_f32_e64 s[88:89], |v3|, s79
	s_nop 1
	v_cndmask_b32_e64 v3, v3, v4, s[88:89]
	v_cndmask_b32_e64 v4, 0, v198, s[0:1]
	v_sub_f32_e32 v3, v3, v4
	v_sub_f32_e32 v171, v2, v3
	v_mul_f32_e64 v3, |v167|, s84
	v_exp_f32_e32 v3, v3
	v_min_f32_e32 v2, 0, v167
	v_fmamk_f32 v168, v171, 0x3d800000, v162
	v_add_f32_e32 v3, 1.0, v3
	v_cmp_gt_f32_e64 s[0:1], s31, v3
	s_nop 1
	v_cndmask_b32_e64 v4, 0, 32, s[0:1]
	v_ldexp_f32 v3, v3, v4
	v_log_f32_e32 v3, v3
	s_nop 0
	v_mul_f32_e32 v4, 0x3f317217, v3
	v_fma_f32 v4, v3, s78, -v4
	v_fmac_f32_e32 v4, 0x3377d1cf, v3
	v_fmac_f32_e32 v4, 0x3f317217, v3
	v_cmp_lt_f32_e64 s[88:89], |v3|, s79
	s_nop 1
	v_cndmask_b32_e64 v3, v3, v4, s[88:89]
	v_cndmask_b32_e64 v4, 0, v198, s[0:1]
	v_sub_f32_e32 v3, v3, v4
	v_sub_f32_e32 v174, v2, v3
	ds_read_b128 v[2:5], v19 offset:33088
	v_fmamk_f32 v167, v174, 0x3d800000, v161
	s_waitcnt lgkmcnt(0)
	v_fma_f32 v169, v60, v2, v69
	v_fma_f32 v170, v61, v2, v68
	v_fmac_f32_e32 v169, v62, v3
	v_fmac_f32_e32 v170, v63, v3
	v_fmac_f32_e32 v169, v64, v4
	v_fmac_f32_e32 v170, v65, v4
	v_fmac_f32_e32 v169, v66, v5
	v_fmac_f32_e32 v170, v67, v5
	ds_read_b128 v[2:5], v19 offset:33104
	s_waitcnt lgkmcnt(0)
	v_fmac_f32_e32 v169, v47, v2
	v_fmac_f32_e32 v170, v46, v2
	v_fmac_f32_e32 v169, v17, v3
	v_fmac_f32_e32 v170, v16, v3
	v_fmac_f32_e32 v169, v52, v4
	v_fmac_f32_e32 v170, v53, v4
	v_fmac_f32_e32 v169, v54, v5
	v_fmac_f32_e32 v170, v55, v5
	ds_read_b128 v[2:5], v19 offset:33120
	s_waitcnt lgkmcnt(0)
	v_fmac_f32_e32 v169, v48, v2
	v_fmac_f32_e32 v170, v49, v2
	v_fmac_f32_e32 v169, v50, v3
	v_fmac_f32_e32 v170, v51, v3
	v_fmac_f32_e32 v169, v56, v4
	v_fmac_f32_e32 v170, v57, v4
	v_fmac_f32_e32 v169, v58, v5
	v_fmac_f32_e32 v170, v59, v5
	ds_read_b128 v[2:5], v19 offset:33136
	s_waitcnt lgkmcnt(0)
	v_fmac_f32_e32 v169, v12, v2
	v_fmac_f32_e32 v169, v6, v3
	v_fmac_f32_e32 v169, v14, v4
	v_fmac_f32_e32 v170, v13, v2
	v_fmac_f32_e32 v169, v9, v5
	v_fmac_f32_e32 v170, v7, v3
	v_mul_f32_e64 v3, |v169|, s84
	v_exp_f32_e32 v3, v3
	v_fmac_f32_e32 v170, v15, v4
	v_fmac_f32_e32 v170, v10, v5
	v_min_f32_e32 v2, 0, v169
	v_add_f32_e32 v3, 1.0, v3
	v_cmp_gt_f32_e64 s[0:1], s31, v3
	s_nop 1
	v_cndmask_b32_e64 v4, 0, 32, s[0:1]
	v_ldexp_f32 v3, v3, v4
	v_log_f32_e32 v3, v3
	s_nop 0
	v_mul_f32_e32 v4, 0x3f317217, v3
	v_fma_f32 v4, v3, s78, -v4
	v_fmac_f32_e32 v4, 0x3377d1cf, v3
	v_fmac_f32_e32 v4, 0x3f317217, v3
	v_cmp_lt_f32_e64 s[88:89], |v3|, s79
	s_nop 1
	v_cndmask_b32_e64 v3, v3, v4, s[88:89]
	v_cndmask_b32_e64 v4, 0, v198, s[0:1]
	v_sub_f32_e32 v3, v3, v4
	v_sub_f32_e32 v177, v2, v3
	v_mul_f32_e64 v3, |v170|, s84
	v_exp_f32_e32 v3, v3
	v_min_f32_e32 v2, 0, v170
	v_fmamk_f32 v170, v177, 0x3d800000, v168
	v_add_f32_e32 v3, 1.0, v3
	v_cmp_gt_f32_e64 s[0:1], s31, v3
	s_nop 1
	v_cndmask_b32_e64 v4, 0, 32, s[0:1]
	v_ldexp_f32 v3, v3, v4
	v_log_f32_e32 v3, v3
	s_nop 0
	v_mul_f32_e32 v4, 0x3f317217, v3
	v_fma_f32 v4, v3, s78, -v4
	v_fmac_f32_e32 v4, 0x3377d1cf, v3
	v_fmac_f32_e32 v4, 0x3f317217, v3
	v_cmp_lt_f32_e64 s[88:89], |v3|, s79
	s_nop 1
	v_cndmask_b32_e64 v3, v3, v4, s[88:89]
	v_cndmask_b32_e64 v4, 0, v198, s[0:1]
	v_sub_f32_e32 v3, v3, v4
	v_sub_f32_e32 v180, v2, v3
	ds_read_b128 v[2:5], v19 offset:33152
	v_fmamk_f32 v169, v180, 0x3d800000, v167
	s_waitcnt lgkmcnt(0)
	v_fma_f32 v172, v60, v2, v69
	v_fma_f32 v173, v61, v2, v68
	v_fmac_f32_e32 v172, v62, v3
	v_fmac_f32_e32 v173, v63, v3
	v_fmac_f32_e32 v172, v64, v4
	v_fmac_f32_e32 v173, v65, v4
	v_fmac_f32_e32 v172, v66, v5
	v_fmac_f32_e32 v173, v67, v5
	ds_read_b128 v[2:5], v19 offset:33168
	s_waitcnt lgkmcnt(0)
	v_fmac_f32_e32 v172, v47, v2
	v_fmac_f32_e32 v173, v46, v2
	v_fmac_f32_e32 v172, v17, v3
	v_fmac_f32_e32 v173, v16, v3
	v_fmac_f32_e32 v172, v52, v4
	v_fmac_f32_e32 v173, v53, v4
	v_fmac_f32_e32 v172, v54, v5
	v_fmac_f32_e32 v173, v55, v5
	ds_read_b128 v[2:5], v19 offset:33184
	s_waitcnt lgkmcnt(0)
	v_fmac_f32_e32 v172, v48, v2
	v_fmac_f32_e32 v173, v49, v2
	v_fmac_f32_e32 v172, v50, v3
	v_fmac_f32_e32 v173, v51, v3
	v_fmac_f32_e32 v172, v56, v4
	v_fmac_f32_e32 v173, v57, v4
	v_fmac_f32_e32 v172, v58, v5
	v_fmac_f32_e32 v173, v59, v5
	ds_read_b128 v[2:5], v19 offset:33200
	s_waitcnt lgkmcnt(0)
	v_fmac_f32_e32 v172, v12, v2
	v_fmac_f32_e32 v172, v6, v3
	v_fmac_f32_e32 v172, v14, v4
	v_fmac_f32_e32 v173, v13, v2
	v_fmac_f32_e32 v172, v9, v5
	v_fmac_f32_e32 v173, v7, v3
	v_mul_f32_e64 v3, |v172|, s84
	v_exp_f32_e32 v3, v3
	v_fmac_f32_e32 v173, v15, v4
	v_fmac_f32_e32 v173, v10, v5
	v_min_f32_e32 v2, 0, v172
	v_add_f32_e32 v3, 1.0, v3
	v_cmp_gt_f32_e64 s[0:1], s31, v3
	s_nop 1
	v_cndmask_b32_e64 v4, 0, 32, s[0:1]
	v_ldexp_f32 v3, v3, v4
	v_log_f32_e32 v3, v3
	s_nop 0
	v_mul_f32_e32 v4, 0x3f317217, v3
	v_fma_f32 v4, v3, s78, -v4
	v_fmac_f32_e32 v4, 0x3377d1cf, v3
	v_fmac_f32_e32 v4, 0x3f317217, v3
	v_cmp_lt_f32_e64 s[88:89], |v3|, s79
	s_nop 1
	v_cndmask_b32_e64 v3, v3, v4, s[88:89]
	v_cndmask_b32_e64 v4, 0, v198, s[0:1]
	v_sub_f32_e32 v3, v3, v4
	v_sub_f32_e32 v183, v2, v3
	v_mul_f32_e64 v3, |v173|, s84
	v_exp_f32_e32 v3, v3
	v_min_f32_e32 v2, 0, v173
	v_fmamk_f32 v173, v183, 0x3d800000, v170
	v_add_f32_e32 v3, 1.0, v3
	v_cmp_gt_f32_e64 s[0:1], s31, v3
	s_nop 1
	v_cndmask_b32_e64 v4, 0, 32, s[0:1]
	v_ldexp_f32 v3, v3, v4
	v_log_f32_e32 v3, v3
	s_nop 0
	v_mul_f32_e32 v4, 0x3f317217, v3
	v_fma_f32 v4, v3, s78, -v4
	v_fmac_f32_e32 v4, 0x3377d1cf, v3
	v_fmac_f32_e32 v4, 0x3f317217, v3
	v_cmp_lt_f32_e64 s[88:89], |v3|, s79
	s_nop 1
	v_cndmask_b32_e64 v3, v3, v4, s[88:89]
	v_cndmask_b32_e64 v4, 0, v198, s[0:1]
	v_sub_f32_e32 v3, v3, v4
	v_sub_f32_e32 v199, v2, v3
	ds_read_b128 v[2:5], v19 offset:33216
	v_fmamk_f32 v172, v199, 0x3d800000, v169
	s_waitcnt lgkmcnt(0)
	v_fma_f32 v175, v60, v2, v69
	v_fma_f32 v176, v61, v2, v68
	v_fmac_f32_e32 v175, v62, v3
	v_fmac_f32_e32 v176, v63, v3
	v_fmac_f32_e32 v175, v64, v4
	v_fmac_f32_e32 v176, v65, v4
	v_fmac_f32_e32 v175, v66, v5
	v_fmac_f32_e32 v176, v67, v5
	ds_read_b128 v[2:5], v19 offset:33232
	s_waitcnt lgkmcnt(0)
	v_fmac_f32_e32 v175, v47, v2
	v_fmac_f32_e32 v176, v46, v2
	v_fmac_f32_e32 v175, v17, v3
	v_fmac_f32_e32 v176, v16, v3
	v_fmac_f32_e32 v175, v52, v4
	v_fmac_f32_e32 v176, v53, v4
	v_fmac_f32_e32 v175, v54, v5
	v_fmac_f32_e32 v176, v55, v5
	ds_read_b128 v[2:5], v19 offset:33248
	s_waitcnt lgkmcnt(0)
	v_fmac_f32_e32 v175, v48, v2
	v_fmac_f32_e32 v176, v49, v2
	v_fmac_f32_e32 v175, v50, v3
	v_fmac_f32_e32 v176, v51, v3
	v_fmac_f32_e32 v175, v56, v4
	v_fmac_f32_e32 v176, v57, v4
	v_fmac_f32_e32 v175, v58, v5
	v_fmac_f32_e32 v176, v59, v5
	ds_read_b128 v[2:5], v19 offset:33264
	s_waitcnt lgkmcnt(0)
	v_fmac_f32_e32 v175, v12, v2
	v_fmac_f32_e32 v175, v6, v3
	v_fmac_f32_e32 v175, v14, v4
	v_fmac_f32_e32 v176, v13, v2
	v_fmac_f32_e32 v175, v9, v5
	v_fmac_f32_e32 v176, v7, v3
	v_mul_f32_e64 v3, |v175|, s84
	v_exp_f32_e32 v3, v3
	v_fmac_f32_e32 v176, v15, v4
	v_fmac_f32_e32 v176, v10, v5
	v_min_f32_e32 v2, 0, v175
	v_add_f32_e32 v3, 1.0, v3
	v_cmp_gt_f32_e64 s[0:1], s31, v3
	s_nop 1
	v_cndmask_b32_e64 v4, 0, 32, s[0:1]
	v_ldexp_f32 v3, v3, v4
	v_log_f32_e32 v3, v3
	s_nop 0
	v_mul_f32_e32 v4, 0x3f317217, v3
	v_fma_f32 v4, v3, s78, -v4
	v_fmac_f32_e32 v4, 0x3377d1cf, v3
	v_fmac_f32_e32 v4, 0x3f317217, v3
	v_cmp_lt_f32_e64 s[88:89], |v3|, s79
	s_nop 1
	v_cndmask_b32_e64 v3, v3, v4, s[88:89]
	v_cndmask_b32_e64 v4, 0, v198, s[0:1]
	v_sub_f32_e32 v3, v3, v4
	v_sub_f32_e32 v202, v2, v3
	v_mul_f32_e64 v3, |v176|, s84
	v_exp_f32_e32 v3, v3
	v_min_f32_e32 v2, 0, v176
	v_fmamk_f32 v176, v202, 0x3d800000, v173
	v_add_f32_e32 v3, 1.0, v3
	v_cmp_gt_f32_e64 s[0:1], s31, v3
	s_nop 1
	v_cndmask_b32_e64 v4, 0, 32, s[0:1]
	v_ldexp_f32 v3, v3, v4
	v_log_f32_e32 v3, v3
	s_nop 0
	v_mul_f32_e32 v4, 0x3f317217, v3
	v_fma_f32 v4, v3, s78, -v4
	v_fmac_f32_e32 v4, 0x3377d1cf, v3
	v_fmac_f32_e32 v4, 0x3f317217, v3
	v_cmp_lt_f32_e64 s[88:89], |v3|, s79
	s_nop 1
	v_cndmask_b32_e64 v3, v3, v4, s[88:89]
	v_cndmask_b32_e64 v4, 0, v198, s[0:1]
	v_sub_f32_e32 v3, v3, v4
	v_sub_f32_e32 v203, v2, v3
	ds_read_b128 v[2:5], v19 offset:33280
	v_fmamk_f32 v175, v203, 0x3d800000, v172
	s_waitcnt lgkmcnt(0)
	v_fma_f32 v178, v60, v2, v69
	v_fma_f32 v179, v61, v2, v68
	v_fmac_f32_e32 v178, v62, v3
	v_fmac_f32_e32 v179, v63, v3
	v_fmac_f32_e32 v178, v64, v4
	v_fmac_f32_e32 v179, v65, v4
	v_fmac_f32_e32 v178, v66, v5
	v_fmac_f32_e32 v179, v67, v5
	ds_read_b128 v[2:5], v19 offset:33296
	s_waitcnt lgkmcnt(0)
	v_fmac_f32_e32 v178, v47, v2
	v_fmac_f32_e32 v179, v46, v2
	v_fmac_f32_e32 v178, v17, v3
	v_fmac_f32_e32 v179, v16, v3
	v_fmac_f32_e32 v178, v52, v4
	v_fmac_f32_e32 v179, v53, v4
	v_fmac_f32_e32 v178, v54, v5
	v_fmac_f32_e32 v179, v55, v5
	ds_read_b128 v[2:5], v19 offset:33312
	s_waitcnt lgkmcnt(0)
	v_fmac_f32_e32 v178, v48, v2
	v_fmac_f32_e32 v179, v49, v2
	v_fmac_f32_e32 v178, v50, v3
	v_fmac_f32_e32 v179, v51, v3
	v_fmac_f32_e32 v178, v56, v4
	v_fmac_f32_e32 v179, v57, v4
	v_fmac_f32_e32 v178, v58, v5
	v_fmac_f32_e32 v179, v59, v5
	ds_read_b128 v[2:5], v19 offset:33328
	s_waitcnt lgkmcnt(0)
	v_fmac_f32_e32 v178, v12, v2
	v_fmac_f32_e32 v178, v6, v3
	v_fmac_f32_e32 v178, v14, v4
	v_fmac_f32_e32 v179, v13, v2
	v_fmac_f32_e32 v178, v9, v5
	v_fmac_f32_e32 v179, v7, v3
	v_mul_f32_e64 v3, |v178|, s84
	v_exp_f32_e32 v3, v3
	v_fmac_f32_e32 v179, v15, v4
	v_fmac_f32_e32 v179, v10, v5
	v_min_f32_e32 v2, 0, v178
	v_add_f32_e32 v3, 1.0, v3
	v_cmp_gt_f32_e64 s[0:1], s31, v3
	s_nop 1
	v_cndmask_b32_e64 v4, 0, 32, s[0:1]
	v_ldexp_f32 v3, v3, v4
	v_log_f32_e32 v3, v3
	s_nop 0
	v_mul_f32_e32 v4, 0x3f317217, v3
	v_fma_f32 v4, v3, s78, -v4
	v_fmac_f32_e32 v4, 0x3377d1cf, v3
	v_fmac_f32_e32 v4, 0x3f317217, v3
	v_cmp_lt_f32_e64 s[88:89], |v3|, s79
	s_nop 1
	v_cndmask_b32_e64 v3, v3, v4, s[88:89]
	v_cndmask_b32_e64 v4, 0, v198, s[0:1]
	v_sub_f32_e32 v3, v3, v4
	v_sub_f32_e32 v206, v2, v3
	v_mul_f32_e64 v3, |v179|, s84
	v_exp_f32_e32 v3, v3
	v_min_f32_e32 v2, 0, v179
	v_fmamk_f32 v179, v206, 0x3d800000, v176
	v_add_f32_e32 v3, 1.0, v3
	v_cmp_gt_f32_e64 s[0:1], s31, v3
	s_nop 1
	v_cndmask_b32_e64 v4, 0, 32, s[0:1]
	v_ldexp_f32 v3, v3, v4
	v_log_f32_e32 v3, v3
	s_nop 0
	v_mul_f32_e32 v4, 0x3f317217, v3
	v_fma_f32 v4, v3, s78, -v4
	v_fmac_f32_e32 v4, 0x3377d1cf, v3
	v_fmac_f32_e32 v4, 0x3f317217, v3
	v_cmp_lt_f32_e64 s[88:89], |v3|, s79
	s_nop 1
	v_cndmask_b32_e64 v3, v3, v4, s[88:89]
	v_cndmask_b32_e64 v4, 0, v198, s[0:1]
	v_sub_f32_e32 v3, v3, v4
	v_sub_f32_e32 v207, v2, v3
	ds_read_b128 v[2:5], v19 offset:33344
	v_fmamk_f32 v178, v207, 0x3d800000, v175
	s_waitcnt lgkmcnt(0)
	v_fma_f32 v181, v60, v2, v69
	v_fma_f32 v182, v61, v2, v68
	v_fmac_f32_e32 v181, v62, v3
	v_fmac_f32_e32 v182, v63, v3
	v_fmac_f32_e32 v181, v64, v4
	v_fmac_f32_e32 v182, v65, v4
	v_fmac_f32_e32 v181, v66, v5
	v_fmac_f32_e32 v182, v67, v5
	ds_read_b128 v[2:5], v19 offset:33360
	s_waitcnt lgkmcnt(0)
	v_fmac_f32_e32 v181, v47, v2
	v_fmac_f32_e32 v182, v46, v2
	v_fmac_f32_e32 v181, v17, v3
	v_fmac_f32_e32 v182, v16, v3
	v_fmac_f32_e32 v181, v52, v4
	v_fmac_f32_e32 v182, v53, v4
	v_fmac_f32_e32 v181, v54, v5
	v_fmac_f32_e32 v182, v55, v5
	ds_read_b128 v[2:5], v19 offset:33376
	s_waitcnt lgkmcnt(0)
	v_fmac_f32_e32 v181, v48, v2
	v_fmac_f32_e32 v182, v49, v2
	v_fmac_f32_e32 v181, v50, v3
	v_fmac_f32_e32 v182, v51, v3
	v_fmac_f32_e32 v181, v56, v4
	v_fmac_f32_e32 v182, v57, v4
	v_fmac_f32_e32 v181, v58, v5
	v_fmac_f32_e32 v182, v59, v5
	ds_read_b128 v[2:5], v19 offset:33392
	s_waitcnt lgkmcnt(0)
	v_fmac_f32_e32 v181, v12, v2
	v_fmac_f32_e32 v181, v6, v3
	v_fmac_f32_e32 v181, v14, v4
	v_fmac_f32_e32 v182, v13, v2
	v_fmac_f32_e32 v181, v9, v5
	v_fmac_f32_e32 v182, v7, v3
	v_mul_f32_e64 v3, |v181|, s84
	v_exp_f32_e32 v3, v3
	v_fmac_f32_e32 v182, v15, v4
	v_fmac_f32_e32 v182, v10, v5
	v_min_f32_e32 v2, 0, v181
	v_add_f32_e32 v3, 1.0, v3
	v_cmp_gt_f32_e64 s[0:1], s31, v3
	s_nop 1
	v_cndmask_b32_e64 v4, 0, 32, s[0:1]
	v_ldexp_f32 v3, v3, v4
	v_log_f32_e32 v3, v3
	s_nop 0
	v_mul_f32_e32 v4, 0x3f317217, v3
	v_fma_f32 v4, v3, s78, -v4
	v_fmac_f32_e32 v4, 0x3377d1cf, v3
	v_fmac_f32_e32 v4, 0x3f317217, v3
	v_cmp_lt_f32_e64 s[88:89], |v3|, s79
	s_nop 1
	v_cndmask_b32_e64 v3, v3, v4, s[88:89]
	v_cndmask_b32_e64 v4, 0, v198, s[0:1]
	v_sub_f32_e32 v3, v3, v4
	v_sub_f32_e32 v210, v2, v3
	v_mul_f32_e64 v3, |v182|, s84
	v_exp_f32_e32 v3, v3
	v_min_f32_e32 v2, 0, v182
	v_fmamk_f32 v182, v210, 0x3d800000, v179
	v_add_f32_e32 v3, 1.0, v3
	v_cmp_gt_f32_e64 s[0:1], s31, v3
	s_nop 1
	v_cndmask_b32_e64 v4, 0, 32, s[0:1]
	v_ldexp_f32 v3, v3, v4
	v_log_f32_e32 v3, v3
	s_nop 0
	v_mul_f32_e32 v4, 0x3f317217, v3
	v_fma_f32 v4, v3, s78, -v4
	v_fmac_f32_e32 v4, 0x3377d1cf, v3
	v_fmac_f32_e32 v4, 0x3f317217, v3
	v_cmp_lt_f32_e64 s[88:89], |v3|, s79
	s_nop 1
	v_cndmask_b32_e64 v3, v3, v4, s[88:89]
	v_cndmask_b32_e64 v4, 0, v198, s[0:1]
	v_sub_f32_e32 v3, v3, v4
	v_sub_f32_e32 v211, v2, v3
	ds_read_b128 v[2:5], v19 offset:33408
	v_fmamk_f32 v181, v211, 0x3d800000, v178
	s_waitcnt lgkmcnt(0)
	v_fma_f32 v192, v60, v2, v69
	v_fma_f32 v193, v61, v2, v68
	v_fmac_f32_e32 v192, v62, v3
	v_fmac_f32_e32 v193, v63, v3
	v_fmac_f32_e32 v192, v64, v4
	v_fmac_f32_e32 v193, v65, v4
	v_fmac_f32_e32 v192, v66, v5
	v_fmac_f32_e32 v193, v67, v5
	ds_read_b128 v[2:5], v19 offset:33424
	s_waitcnt lgkmcnt(0)
	v_fmac_f32_e32 v192, v47, v2
	v_fmac_f32_e32 v193, v46, v2
	v_fmac_f32_e32 v192, v17, v3
	v_fmac_f32_e32 v193, v16, v3
	v_fmac_f32_e32 v192, v52, v4
	v_fmac_f32_e32 v193, v53, v4
	v_fmac_f32_e32 v192, v54, v5
	v_fmac_f32_e32 v193, v55, v5
	ds_read_b128 v[2:5], v19 offset:33440
	s_waitcnt lgkmcnt(0)
	v_fmac_f32_e32 v192, v48, v2
	v_fmac_f32_e32 v193, v49, v2
	v_fmac_f32_e32 v192, v50, v3
	v_fmac_f32_e32 v193, v51, v3
	v_fmac_f32_e32 v192, v56, v4
	v_fmac_f32_e32 v193, v57, v4
	v_fmac_f32_e32 v192, v58, v5
	v_fmac_f32_e32 v193, v59, v5
	ds_read_b128 v[2:5], v19 offset:33456
	s_waitcnt lgkmcnt(0)
	v_fmac_f32_e32 v192, v12, v2
	v_fmac_f32_e32 v192, v6, v3
	v_fmac_f32_e32 v192, v14, v4
	v_fmac_f32_e32 v193, v13, v2
	v_fmac_f32_e32 v192, v9, v5
	v_fmac_f32_e32 v193, v7, v3
	v_mul_f32_e64 v3, |v192|, s84
	v_exp_f32_e32 v3, v3
	v_fmac_f32_e32 v193, v15, v4
	v_fmac_f32_e32 v193, v10, v5
	v_min_f32_e32 v2, 0, v192
	v_add_f32_e32 v3, 1.0, v3
	v_cmp_gt_f32_e64 s[0:1], s31, v3
	s_nop 1
	v_cndmask_b32_e64 v4, 0, 32, s[0:1]
	v_ldexp_f32 v3, v3, v4
	v_log_f32_e32 v3, v3
	s_nop 0
	v_mul_f32_e32 v4, 0x3f317217, v3
	v_fma_f32 v4, v3, s78, -v4
	v_fmac_f32_e32 v4, 0x3377d1cf, v3
	v_fmac_f32_e32 v4, 0x3f317217, v3
	v_cmp_lt_f32_e64 s[88:89], |v3|, s79
	s_nop 1
	v_cndmask_b32_e64 v3, v3, v4, s[88:89]
	v_cndmask_b32_e64 v4, 0, v198, s[0:1]
	v_sub_f32_e32 v3, v3, v4
	v_sub_f32_e32 v214, v2, v3
	v_mul_f32_e64 v3, |v193|, s84
	v_exp_f32_e32 v3, v3
	v_min_f32_e32 v2, 0, v193
	v_fmamk_f32 v201, v214, 0x3d800000, v182
	v_add_f32_e32 v3, 1.0, v3
	v_cmp_gt_f32_e64 s[0:1], s31, v3
	s_nop 1
	v_cndmask_b32_e64 v4, 0, 32, s[0:1]
	v_ldexp_f32 v3, v3, v4
	v_log_f32_e32 v3, v3
	s_nop 0
	v_mul_f32_e32 v4, 0x3f317217, v3
	v_fma_f32 v4, v3, s78, -v4
	v_fmac_f32_e32 v4, 0x3377d1cf, v3
	v_fmac_f32_e32 v4, 0x3f317217, v3
	v_cmp_lt_f32_e64 s[88:89], |v3|, s79
	s_nop 1
	v_cndmask_b32_e64 v3, v3, v4, s[88:89]
	v_cndmask_b32_e64 v4, 0, v198, s[0:1]
	v_sub_f32_e32 v3, v3, v4
	v_sub_f32_e32 v217, v2, v3
	ds_read_b128 v[2:5], v19 offset:33472
	v_fmamk_f32 v200, v217, 0x3d800000, v181
	s_waitcnt lgkmcnt(0)
	v_fma_f32 v192, v60, v2, v69
	v_fma_f32 v193, v61, v2, v68
	v_fmac_f32_e32 v192, v62, v3
	v_fmac_f32_e32 v193, v63, v3
	v_fmac_f32_e32 v192, v64, v4
	v_fmac_f32_e32 v193, v65, v4
	v_fmac_f32_e32 v192, v66, v5
	v_fmac_f32_e32 v193, v67, v5
	ds_read_b128 v[2:5], v19 offset:33488
	s_waitcnt lgkmcnt(0)
	v_fmac_f32_e32 v192, v47, v2
	v_fmac_f32_e32 v193, v46, v2
	v_fmac_f32_e32 v192, v17, v3
	v_fmac_f32_e32 v193, v16, v3
	v_fmac_f32_e32 v192, v52, v4
	v_fmac_f32_e32 v193, v53, v4
	v_fmac_f32_e32 v192, v54, v5
	v_fmac_f32_e32 v193, v55, v5
	ds_read_b128 v[2:5], v19 offset:33504
	s_waitcnt lgkmcnt(0)
	v_fmac_f32_e32 v192, v48, v2
	v_fmac_f32_e32 v193, v49, v2
	v_fmac_f32_e32 v192, v50, v3
	v_fmac_f32_e32 v193, v51, v3
	v_fmac_f32_e32 v192, v56, v4
	v_fmac_f32_e32 v193, v57, v4
	v_fmac_f32_e32 v192, v58, v5
	v_fmac_f32_e32 v193, v59, v5
	ds_read_b128 v[2:5], v19 offset:33520
	s_waitcnt lgkmcnt(0)
	v_fmac_f32_e32 v192, v12, v2
	v_fmac_f32_e32 v192, v6, v3
	v_fmac_f32_e32 v192, v14, v4
	v_fmac_f32_e32 v193, v13, v2
	v_fmac_f32_e32 v192, v9, v5
	v_fmac_f32_e32 v193, v7, v3
	v_mul_f32_e64 v3, |v192|, s84
	v_exp_f32_e32 v3, v3
	v_fmac_f32_e32 v193, v15, v4
	v_fmac_f32_e32 v193, v10, v5
	v_min_f32_e32 v2, 0, v192
	v_add_f32_e32 v3, 1.0, v3
	v_cmp_gt_f32_e64 s[0:1], s31, v3
	s_nop 1
	v_cndmask_b32_e64 v4, 0, 32, s[0:1]
	v_ldexp_f32 v3, v3, v4
	v_log_f32_e32 v3, v3
	s_nop 0
	v_mul_f32_e32 v4, 0x3f317217, v3
	v_fma_f32 v4, v3, s78, -v4
	v_fmac_f32_e32 v4, 0x3377d1cf, v3
	v_fmac_f32_e32 v4, 0x3f317217, v3
	v_cmp_lt_f32_e64 s[88:89], |v3|, s79
	s_nop 1
	v_cndmask_b32_e64 v3, v3, v4, s[88:89]
	v_cndmask_b32_e64 v4, 0, v198, s[0:1]
	v_sub_f32_e32 v3, v3, v4
	v_sub_f32_e32 v218, v2, v3
	v_mul_f32_e64 v3, |v193|, s84
	v_exp_f32_e32 v3, v3
	v_min_f32_e32 v2, 0, v193
	v_fmamk_f32 v205, v218, 0x3d800000, v201
	v_add_f32_e32 v3, 1.0, v3
	v_cmp_gt_f32_e64 s[0:1], s31, v3
	s_nop 1
	v_cndmask_b32_e64 v4, 0, 32, s[0:1]
	v_ldexp_f32 v3, v3, v4
	v_log_f32_e32 v3, v3
	s_nop 0
	v_mul_f32_e32 v4, 0x3f317217, v3
	v_fma_f32 v4, v3, s78, -v4
	v_fmac_f32_e32 v4, 0x3377d1cf, v3
	v_fmac_f32_e32 v4, 0x3f317217, v3
	v_cmp_lt_f32_e64 s[88:89], |v3|, s79
	s_nop 1
	v_cndmask_b32_e64 v3, v3, v4, s[88:89]
	v_cndmask_b32_e64 v4, 0, v198, s[0:1]
	v_sub_f32_e32 v3, v3, v4
	v_sub_f32_e32 v223, v2, v3
	ds_read_b128 v[2:5], v19 offset:33536
	v_fmamk_f32 v204, v223, 0x3d800000, v200
	s_waitcnt lgkmcnt(0)
	v_fma_f32 v192, v60, v2, v69
	v_fma_f32 v193, v61, v2, v68
	v_fmac_f32_e32 v192, v62, v3
	v_fmac_f32_e32 v193, v63, v3
	v_fmac_f32_e32 v192, v64, v4
	v_fmac_f32_e32 v193, v65, v4
	v_fmac_f32_e32 v192, v66, v5
	v_fmac_f32_e32 v193, v67, v5
	ds_read_b128 v[2:5], v19 offset:33552
	s_waitcnt lgkmcnt(0)
	v_fmac_f32_e32 v192, v47, v2
	v_fmac_f32_e32 v193, v46, v2
	v_fmac_f32_e32 v192, v17, v3
	v_fmac_f32_e32 v193, v16, v3
	v_fmac_f32_e32 v192, v52, v4
	v_fmac_f32_e32 v193, v53, v4
	v_fmac_f32_e32 v192, v54, v5
	v_fmac_f32_e32 v193, v55, v5
	ds_read_b128 v[2:5], v19 offset:33568
	s_waitcnt lgkmcnt(0)
	v_fmac_f32_e32 v192, v48, v2
	v_fmac_f32_e32 v193, v49, v2
	v_fmac_f32_e32 v192, v50, v3
	v_fmac_f32_e32 v193, v51, v3
	v_fmac_f32_e32 v192, v56, v4
	v_fmac_f32_e32 v193, v57, v4
	v_fmac_f32_e32 v192, v58, v5
	v_fmac_f32_e32 v193, v59, v5
	ds_read_b128 v[2:5], v19 offset:33584
	s_waitcnt lgkmcnt(0)
	v_fmac_f32_e32 v192, v12, v2
	v_fmac_f32_e32 v192, v6, v3
	v_fmac_f32_e32 v192, v14, v4
	v_fmac_f32_e32 v193, v13, v2
	v_fmac_f32_e32 v192, v9, v5
	v_fmac_f32_e32 v193, v7, v3
	v_mul_f32_e64 v3, |v192|, s84
	v_exp_f32_e32 v3, v3
	v_fmac_f32_e32 v193, v15, v4
	v_fmac_f32_e32 v193, v10, v5
	v_min_f32_e32 v2, 0, v192
	v_add_f32_e32 v3, 1.0, v3
	v_cmp_gt_f32_e64 s[0:1], s31, v3
	s_nop 1
	v_cndmask_b32_e64 v4, 0, 32, s[0:1]
	v_ldexp_f32 v3, v3, v4
	v_log_f32_e32 v3, v3
	s_nop 0
	v_mul_f32_e32 v4, 0x3f317217, v3
	v_fma_f32 v4, v3, s78, -v4
	v_fmac_f32_e32 v4, 0x3377d1cf, v3
	v_fmac_f32_e32 v4, 0x3f317217, v3
	v_cmp_lt_f32_e64 s[88:89], |v3|, s79
	s_nop 1
	v_cndmask_b32_e64 v3, v3, v4, s[88:89]
	v_cndmask_b32_e64 v4, 0, v198, s[0:1]
	v_sub_f32_e32 v3, v3, v4
	v_sub_f32_e32 v224, v2, v3
	v_mul_f32_e64 v3, |v193|, s84
	v_exp_f32_e32 v3, v3
	v_min_f32_e32 v2, 0, v193
	v_fmamk_f32 v209, v224, 0x3d800000, v205
	v_add_f32_e32 v3, 1.0, v3
	v_cmp_gt_f32_e64 s[0:1], s31, v3
	s_nop 1
	v_cndmask_b32_e64 v4, 0, 32, s[0:1]
	v_ldexp_f32 v3, v3, v4
	v_log_f32_e32 v3, v3
	s_nop 0
	v_mul_f32_e32 v4, 0x3f317217, v3
	v_fma_f32 v4, v3, s78, -v4
	v_fmac_f32_e32 v4, 0x3377d1cf, v3
	v_fmac_f32_e32 v4, 0x3f317217, v3
	v_cmp_lt_f32_e64 s[88:89], |v3|, s79
	s_nop 1
	v_cndmask_b32_e64 v3, v3, v4, s[88:89]
	v_cndmask_b32_e64 v4, 0, v198, s[0:1]
	v_sub_f32_e32 v3, v3, v4
	v_sub_f32_e32 v225, v2, v3
	ds_read_b128 v[2:5], v19 offset:33600
	v_fmamk_f32 v208, v225, 0x3d800000, v204
	s_waitcnt lgkmcnt(0)
	v_fma_f32 v192, v60, v2, v69
	v_fma_f32 v193, v61, v2, v68
	v_fmac_f32_e32 v192, v62, v3
	v_fmac_f32_e32 v193, v63, v3
	v_fmac_f32_e32 v192, v64, v4
	v_fmac_f32_e32 v193, v65, v4
	v_fmac_f32_e32 v192, v66, v5
	v_fmac_f32_e32 v193, v67, v5
	ds_read_b128 v[2:5], v19 offset:33616
	s_waitcnt lgkmcnt(0)
	v_fmac_f32_e32 v192, v47, v2
	v_fmac_f32_e32 v193, v46, v2
	v_fmac_f32_e32 v192, v17, v3
	v_fmac_f32_e32 v193, v16, v3
	v_fmac_f32_e32 v192, v52, v4
	v_fmac_f32_e32 v193, v53, v4
	v_fmac_f32_e32 v192, v54, v5
	v_fmac_f32_e32 v193, v55, v5
	ds_read_b128 v[2:5], v19 offset:33632
	s_waitcnt lgkmcnt(0)
	v_fmac_f32_e32 v192, v48, v2
	v_fmac_f32_e32 v193, v49, v2
	v_fmac_f32_e32 v192, v50, v3
	v_fmac_f32_e32 v193, v51, v3
	v_fmac_f32_e32 v192, v56, v4
	v_fmac_f32_e32 v193, v57, v4
	v_fmac_f32_e32 v192, v58, v5
	v_fmac_f32_e32 v193, v59, v5
	ds_read_b128 v[2:5], v19 offset:33648
	s_waitcnt lgkmcnt(0)
	v_fmac_f32_e32 v192, v12, v2
	v_fmac_f32_e32 v192, v6, v3
	v_fmac_f32_e32 v192, v14, v4
	v_fmac_f32_e32 v193, v13, v2
	v_fmac_f32_e32 v192, v9, v5
	v_fmac_f32_e32 v193, v7, v3
	v_mul_f32_e64 v3, |v192|, s84
	v_exp_f32_e32 v3, v3
	v_fmac_f32_e32 v193, v15, v4
	v_fmac_f32_e32 v193, v10, v5
	v_min_f32_e32 v2, 0, v192
	v_add_f32_e32 v3, 1.0, v3
	v_cmp_gt_f32_e64 s[0:1], s31, v3
	s_nop 1
	v_cndmask_b32_e64 v4, 0, 32, s[0:1]
	v_ldexp_f32 v3, v3, v4
	v_log_f32_e32 v3, v3
	s_nop 0
	v_mul_f32_e32 v4, 0x3f317217, v3
	v_fma_f32 v4, v3, s78, -v4
	v_fmac_f32_e32 v4, 0x3377d1cf, v3
	v_fmac_f32_e32 v4, 0x3f317217, v3
	v_cmp_lt_f32_e64 s[88:89], |v3|, s79
	s_nop 1
	v_cndmask_b32_e64 v3, v3, v4, s[88:89]
	v_cndmask_b32_e64 v4, 0, v198, s[0:1]
	v_sub_f32_e32 v3, v3, v4
	v_sub_f32_e32 v226, v2, v3
	v_mul_f32_e64 v3, |v193|, s84
	v_exp_f32_e32 v3, v3
	v_min_f32_e32 v2, 0, v193
	v_fmamk_f32 v213, v226, 0x3d800000, v209
	v_add_f32_e32 v3, 1.0, v3
	v_cmp_gt_f32_e64 s[0:1], s31, v3
	s_nop 1
	v_cndmask_b32_e64 v4, 0, 32, s[0:1]
	v_ldexp_f32 v3, v3, v4
	v_log_f32_e32 v3, v3
	s_nop 0
	v_mul_f32_e32 v4, 0x3f317217, v3
	v_fma_f32 v4, v3, s78, -v4
	v_fmac_f32_e32 v4, 0x3377d1cf, v3
	v_fmac_f32_e32 v4, 0x3f317217, v3
	v_cmp_lt_f32_e64 s[88:89], |v3|, s79
	s_nop 1
	v_cndmask_b32_e64 v3, v3, v4, s[88:89]
	v_cndmask_b32_e64 v4, 0, v198, s[0:1]
	v_sub_f32_e32 v3, v3, v4
	v_sub_f32_e32 v227, v2, v3
	ds_read_b128 v[2:5], v19 offset:33664
	v_fmamk_f32 v212, v227, 0x3d800000, v208
	s_waitcnt lgkmcnt(0)
	v_fma_f32 v192, v60, v2, v69
	v_fma_f32 v193, v61, v2, v68
	v_fmac_f32_e32 v192, v62, v3
	v_fmac_f32_e32 v193, v63, v3
	v_fmac_f32_e32 v192, v64, v4
	v_fmac_f32_e32 v193, v65, v4
	v_fmac_f32_e32 v192, v66, v5
	v_fmac_f32_e32 v193, v67, v5
	ds_read_b128 v[2:5], v19 offset:33680
	s_waitcnt lgkmcnt(0)
	v_fmac_f32_e32 v192, v47, v2
	v_fmac_f32_e32 v193, v46, v2
	v_fmac_f32_e32 v192, v17, v3
	v_fmac_f32_e32 v193, v16, v3
	v_fmac_f32_e32 v192, v52, v4
	v_fmac_f32_e32 v193, v53, v4
	v_fmac_f32_e32 v192, v54, v5
	v_fmac_f32_e32 v193, v55, v5
	ds_read_b128 v[2:5], v19 offset:33696
	s_waitcnt lgkmcnt(0)
	v_fmac_f32_e32 v192, v48, v2
	v_fmac_f32_e32 v193, v49, v2
	v_fmac_f32_e32 v192, v50, v3
	v_fmac_f32_e32 v193, v51, v3
	v_fmac_f32_e32 v192, v56, v4
	v_fmac_f32_e32 v193, v57, v4
	v_fmac_f32_e32 v192, v58, v5
	v_fmac_f32_e32 v193, v59, v5
	ds_read_b128 v[2:5], v19 offset:33712
	s_waitcnt lgkmcnt(0)
	v_fmac_f32_e32 v192, v12, v2
	v_fmac_f32_e32 v192, v6, v3
	v_fmac_f32_e32 v192, v14, v4
	v_fmac_f32_e32 v193, v13, v2
	v_fmac_f32_e32 v192, v9, v5
	v_fmac_f32_e32 v193, v7, v3
	v_mul_f32_e64 v3, |v192|, s84
	v_exp_f32_e32 v3, v3
	v_fmac_f32_e32 v193, v15, v4
	v_fmac_f32_e32 v193, v10, v5
	v_min_f32_e32 v2, 0, v192
	v_add_f32_e32 v3, 1.0, v3
	v_cmp_gt_f32_e64 s[0:1], s31, v3
	s_nop 1
	v_cndmask_b32_e64 v4, 0, 32, s[0:1]
	v_ldexp_f32 v3, v3, v4
	v_log_f32_e32 v3, v3
	s_nop 0
	v_mul_f32_e32 v4, 0x3f317217, v3
	v_fma_f32 v4, v3, s78, -v4
	v_fmac_f32_e32 v4, 0x3377d1cf, v3
	v_fmac_f32_e32 v4, 0x3f317217, v3
	v_cmp_lt_f32_e64 s[88:89], |v3|, s79
	s_nop 1
	v_cndmask_b32_e64 v3, v3, v4, s[88:89]
	v_cndmask_b32_e64 v4, 0, v198, s[0:1]
	v_sub_f32_e32 v3, v3, v4
	v_sub_f32_e32 v228, v2, v3
	v_mul_f32_e64 v3, |v193|, s84
	v_exp_f32_e32 v3, v3
	v_min_f32_e32 v2, 0, v193
	v_fmamk_f32 v216, v228, 0x3d800000, v213
	v_add_f32_e32 v3, 1.0, v3
	v_cmp_gt_f32_e64 s[0:1], s31, v3
	s_nop 1
	v_cndmask_b32_e64 v4, 0, 32, s[0:1]
	v_ldexp_f32 v3, v3, v4
	v_log_f32_e32 v3, v3
	s_nop 0
	v_mul_f32_e32 v4, 0x3f317217, v3
	v_fma_f32 v4, v3, s78, -v4
	v_fmac_f32_e32 v4, 0x3377d1cf, v3
	v_fmac_f32_e32 v4, 0x3f317217, v3
	v_cmp_lt_f32_e64 s[88:89], |v3|, s79
	s_nop 1
	v_cndmask_b32_e64 v3, v3, v4, s[88:89]
	v_cndmask_b32_e64 v4, 0, v198, s[0:1]
	v_sub_f32_e32 v3, v3, v4
	v_sub_f32_e32 v229, v2, v3
	ds_read_b128 v[2:5], v19 offset:33728
	v_fmamk_f32 v215, v229, 0x3d800000, v212
	s_waitcnt lgkmcnt(0)
	v_fmac_f32_e32 v69, v60, v2
	v_fmac_f32_e32 v68, v61, v2
	v_fmac_f32_e32 v69, v62, v3
	v_fmac_f32_e32 v68, v63, v3
	v_fmac_f32_e32 v69, v64, v4
	v_fmac_f32_e32 v68, v65, v4
	v_fmac_f32_e32 v69, v66, v5
	v_fmac_f32_e32 v68, v67, v5
	ds_read_b128 v[2:5], v19 offset:33744
	s_waitcnt lgkmcnt(0)
	v_fmac_f32_e32 v69, v47, v2
	v_fmac_f32_e32 v68, v46, v2
	v_fmac_f32_e32 v69, v17, v3
	v_fmac_f32_e32 v68, v16, v3
	v_fmac_f32_e32 v69, v52, v4
	v_fmac_f32_e32 v68, v53, v4
	v_fmac_f32_e32 v69, v54, v5
	v_fmac_f32_e32 v68, v55, v5
	ds_read_b128 v[2:5], v19 offset:33760
	v_mov_b64_e32 v[46:47], s[58:59]
	s_waitcnt lgkmcnt(0)
	v_fmac_f32_e32 v69, v48, v2
	v_fmac_f32_e32 v68, v49, v2
	v_fmac_f32_e32 v69, v50, v3
	v_fmac_f32_e32 v68, v51, v3
	v_fmac_f32_e32 v69, v56, v4
	v_fmac_f32_e32 v68, v57, v4
	v_fmac_f32_e32 v69, v58, v5
	v_fmac_f32_e32 v68, v59, v5
	ds_read_b128 v[2:5], v19 offset:33776
	s_waitcnt lgkmcnt(0)
	v_fmac_f32_e32 v69, v12, v2
	v_fmac_f32_e32 v69, v6, v3
	v_fmac_f32_e32 v69, v14, v4
	v_fmac_f32_e32 v68, v13, v2
	v_fmac_f32_e32 v69, v9, v5
	v_fmac_f32_e32 v68, v7, v3
	v_mul_f32_e64 v3, |v69|, s84
	v_exp_f32_e32 v3, v3
	v_fmac_f32_e32 v68, v15, v4
	v_fmac_f32_e32 v68, v10, v5
	v_min_f32_e32 v2, 0, v69
	v_add_f32_e32 v3, 1.0, v3
	v_cmp_gt_f32_e64 s[0:1], s31, v3
	s_nop 1
	v_cndmask_b32_e64 v4, 0, 32, s[0:1]
	v_ldexp_f32 v3, v3, v4
	v_log_f32_e32 v3, v3
	s_nop 0
	v_mul_f32_e32 v4, 0x3f317217, v3
	v_fma_f32 v4, v3, s78, -v4
	v_fmac_f32_e32 v4, 0x3377d1cf, v3
	v_fmac_f32_e32 v4, 0x3f317217, v3
	v_cmp_lt_f32_e64 s[88:89], |v3|, s79
	s_nop 1
	v_cndmask_b32_e64 v3, v3, v4, s[88:89]
	v_cndmask_b32_e64 v4, 0, v198, s[0:1]
	v_sub_f32_e32 v3, v3, v4
	v_sub_f32_e32 v9, v2, v3
	v_mul_f32_e64 v3, |v68|, s84
	v_exp_f32_e32 v3, v3
	v_min_f32_e32 v2, 0, v68
	v_fmamk_f32 v220, v9, 0x3d800000, v216
	v_add_f32_e32 v3, 1.0, v3
	v_cmp_gt_f32_e64 s[0:1], s31, v3
	s_nop 1
	v_cndmask_b32_e64 v4, 0, 32, s[0:1]
	v_ldexp_f32 v3, v3, v4
	v_log_f32_e32 v3, v3
	s_nop 0
	v_mul_f32_e32 v4, 0x3f317217, v3
	v_fma_f32 v4, v3, s78, -v4
	v_fmac_f32_e32 v4, 0x3377d1cf, v3
	v_fmac_f32_e32 v4, 0x3f317217, v3
	v_cmp_lt_f32_e64 s[88:89], |v3|, s79
	s_nop 1
	v_cndmask_b32_e64 v3, v3, v4, s[88:89]
	v_cndmask_b32_e64 v4, 0, v198, s[0:1]
	v_sub_f32_e32 v3, v3, v4
	v_sub_f32_e32 v14, v2, v3
	v_fmamk_f32 v219, v14, 0x3d800000, v215
	ds_write2st64_b32 v23, v220, v219 offset0:144 offset1:145
	s_waitcnt lgkmcnt(0)
	s_barrier
	ds_read2st64_b32 v[2:3], v22 offset0:144 offset1:145
	ds_read2st64_b32 v[6:7], v22 offset0:146 offset1:147
	ds_read2st64_b32 v[4:5], v22 offset0:148 offset1:149
	s_waitcnt lgkmcnt(2)
	v_add_f32_e32 v10, 0, v2
	v_add_f32_e32 v13, 0, v3
	s_waitcnt lgkmcnt(1)
	v_add_f32_e32 v2, v10, v6
	v_add_f32_e32 v3, v13, v7
	s_waitcnt lgkmcnt(0)
	v_add_f32_e32 v12, v2, v4
	v_add_f32_e32 v15, v3, v5
	ds_read2st64_b32 v[2:3], v22 offset0:150 offset1:151
	s_waitcnt lgkmcnt(0)
	v_add_f32_e32 v12, v12, v2
	v_add_f32_e32 v15, v15, v3
	v_mul_f32_e32 v12, 0x3fb8aa3b, v12
	v_exp_f32_e32 v221, v12
	v_mul_f32_e32 v12, 0x3fb8aa3b, v15
	v_exp_f32_e32 v222, v12
	s_and_saveexec_b64 s[0:1], s[6:7]
	s_cbranch_execz .LBB0_224
	s_ashr_i32 s5, s58, 31
	s_mov_b32 s4, s58
	v_mov_b64_e32 v[46:47], s[4:5]
	global_store_dword v[36:37], v221, off
	global_store_dword v[36:37], v222, off offset:256
	s_branch .LBB0_224
